# xcd barriers: every arriving workgroup issues buffer_wbl2 sc1 + vmcnt(0) before its arrival atomic so the L2 write-back overlaps the wait for stragglers
# baseline (speedup 1.0000x reference)
; __device__ __forceinline__ unsigned xb_ld(unsigned* p)              { return __hip_atomic_load(p, __ATOMIC_RELAXED, __HIP_MEMORY_SCOPE_AGENT); }
; __device__ __forceinline__ unsigned xb_add(unsigned* p, unsigned v) { return __hip_atomic_fetch_add(p, v, __ATOMIC_RELAXED, __HIP_MEMORY_SCOPE_AGENT); }
; #define XB_SPIN(cond, bar) do { unsigned _sp = 0; while (cond) { __builtin_amdgcn_s_sleep(1); \
;     if ((++_sp & 255u) == 0u) { if (xb_ld(&(bar)[XB_TMO])) break; if (_sp > XB_SPIN_CAP) { atomicAdd(&(bar)[XB_TMO], 1u); break; } } } } while (0)
; __device__ __forceinline__ void xcd_barrier(const XcdBarrier& b) {
;     asm volatile("s_waitcnt vmcnt(0)" ::: "memory");
;     __syncthreads();
;     if (threadIdx.x == 0) {
;         unsigned* bar = b.bar;
;         __builtin_amdgcn_s_waitcnt(0);
;         unsigned nloc = b.st[0], nx = b.st[1];
;         if (nloc == 0u) { xcd_barrier_complete(bar, b.x, nloc, nx); b.st[0] = nloc; b.st[1] = nx; }
;         const unsigned old = xb_add(&bar[XB_XSUB(b.x)], 1u);
;         const unsigned gen = old / nloc;
;         if (old + 1u == (gen + 1u) * nloc) {
;             __builtin_amdgcn_fence(__ATOMIC_RELEASE, "agent");
;             asm volatile("s_waitcnt vmcnt(0)" ::: "memory");
;             const unsigned og = xb_add(&bar[XB_TOP], 1u);
;             const unsigned tg = og / nx;
;             if (og + 1u == (tg + 1u) * nx) xb_add(&bar[XB_TOPGEN], 1u);
;             else XB_SPIN(xb_ld(&bar[XB_TOPGEN]) == tg, bar);
;             __builtin_amdgcn_fence(__ATOMIC_ACQUIRE, "agent");
;             xb_add(&bar[XB_XGEN(b.x)], 1u);
;             asm volatile("s_waitcnt vmcnt(0)" ::: "memory");
;         } else {
;             XB_SPIN(xb_ld(&bar[XB_XGEN(b.x)]) == gen, bar);
;             __builtin_amdgcn_fence(__ATOMIC_ACQUIRE, "agent");
;             asm volatile("s_waitcnt vmcnt(0)" ::: "memory");
;         }
.LBB0_96:
	v_readlane_b32 s3, v254, 45
	s_lshl_b32 s3, s3, 8
	v_readlane_b32 s6, v254, 43
	v_readlane_b32 s7, v254, 44
	s_add_u32 s6, s6, s3
	s_addc_u32 s7, s7, 0
	v_mov_b32_e32 v1, 0x1000
	v_mov_b32_e32 v3, 1
	v_sub_u32_e32 v4, 0, v2
	buffer_wbl2 sc1
	s_waitcnt vmcnt(0)
	global_atomic_add v3, v1, v3, s[6:7] offset:1024 sc0
	v_cvt_f32_u32_e32 v1, v2
	v_rcp_iflag_f32_e32 v1, v1
	s_nop 0
	v_mul_f32_e32 v1, 0x4f7ffffe, v1
	v_cvt_u32_f32_e32 v1, v1
	v_mul_lo_u32 v4, v4, v1
	v_mul_hi_u32 v4, v1, v4
	v_add_u32_e32 v1, v1, v4
	s_waitcnt vmcnt(0)
	v_mul_hi_u32 v1, v3, v1
	v_mul_lo_u32 v4, v1, v2
	v_sub_u32_e32 v4, v3, v4
	v_add_u32_e32 v5, 1, v1
	v_cmp_ge_u32_e32 vcc, v4, v2
	v_add_u32_e32 v3, 1, v3
	s_nop 0
	v_cndmask_b32_e32 v1, v1, v5, vcc
	v_sub_u32_e32 v5, v4, v2
	v_cndmask_b32_e32 v4, v4, v5, vcc
	v_add_u32_e32 v5, 1, v1
	v_cmp_ge_u32_e32 vcc, v4, v2
	s_nop 1
	v_cndmask_b32_e32 v1, v1, v5, vcc
	v_mul_lo_u32 v4, v2, v1
	v_add_u32_e32 v2, v4, v2
	v_cmp_ne_u32_e32 vcc, v3, v2
	s_and_saveexec_b64 s[8:9], vcc
	s_xor_b64 s[8:9], exec, s[8:9]
	s_cbranch_execz .LBB0_110
	s_waitcnt lgkmcnt(0)
	v_mov_b32_e32 v0, 0x2000
	global_load_dword v0, v0, s[6:7] offset:1024 sc1
	s_add_u32 s14, s6, 0x2400
	s_addc_u32 s15, s7, 0
	s_waitcnt vmcnt(0)
	v_cmp_eq_u32_e32 vcc, v0, v1
	s_and_saveexec_b64 s[10:11], vcc
	s_cbranch_execz .LBB0_109
	s_add_u32 s12, s78, 0x193e0200
	s_addc_u32 s13, s79, 0
	s_mov_b32 s3, 1
	s_mov_b64 s[16:17], 0
	v_mov_b32_e32 v0, 0
	s_branch .LBB0_100
